# v44 + PV first LDS reads hoisted above the row-max tree (2 of 4 attention loops)
# speedup vs baseline: 1.0011x; 1.0011x over previous
; #define LAS __attribute__((address_space(3)))
; #define MAX2(a, b) __builtin_amdgcn_fmed3f((a), (b), big_)
; template <bool MLA, bool grpB>
; __device__ __forceinline__ void attn_unit_g(LAS unsigned char* lds, const AttnPtrs& P, int b, int h, int qblk) {
;     ...
;     auto sm = [&](int j) {
;         if (j >= my_last) {
;             if (MLA) { if (j > my_last) {
; #pragma unroll
;                 for (int r = 0; r < 16; ++r) { sc[0][r] = -2e30f; sc[1][r] = -2e30f; } } }
;             else { const int qpos = q0 + r32;
; #pragma unroll
;                 for (int blk = 0; blk < 2; ++blk)
; #pragma unroll
;                     for (int r = 0; r < 16; ++r) { const int key = 64 * j + 32 * blk + 16 * hi + r; if (key > qpos) sc[blk][r] = -2e30f; } }
;         }
;         float big_ = 3.0e38f; asm volatile("" : "+v"(big_));
;         float mxa = MAX2(sc[0][0], sc[0][1]), mxb = MAX2(sc[0][2], sc[0][3]), mxc = MAX2(sc[1][0], sc[1][1]), mxd = MAX2(sc[1][2], sc[1][3]);
; #pragma unroll
;         for (int r = 4; r < 16; r += 4) { mxa = MAX2(mxa, MAX2(sc[0][r], sc[0][r + 1])); mxb = MAX2(mxb, MAX2(sc[0][r + 2], sc[0][r + 3])); mxc = MAX2(mxc, MAX2(sc[1][r], sc[1][r + 1])); mxd = MAX2(mxd, MAX2(sc[1][r + 2], sc[1][r + 3])); }
;         float mx = MAX2(MAX2(mxa, mxb), MAX2(mxc, mxd));
;         mx = MAX2(mx, __shfl_xor(mx, 32));
;         if (__any(mx > mref + 8.0f)) {
;             const float mnew = fmaxf(mref, mx), f = __builtin_amdgcn_exp2f(mref - mnew);
;             mref = mnew; lrun *= f;
; #pragma unroll
;             for (int i = 0; i < 4; ++i)
; #pragma unroll
;                 for (int r = 0; r < 16; ++r) o[i][r] *= f;
;         }
;     ...
;         const LAS unsigned char* va = lds + varow + voff;
;         bf16x8 a[PFD];
;         auto ld = [&](int i) -> bf16x8 {
;             const int dvb = i & 3, bk = i >> 2, so = ((4 * (bk >> 1) + 2 * hi + (bk & 1)) ^ vswz) * 16;
;             return *(const LAS bf16x8*)(va + 32 * dvb * VROW + so);
;         };
; #pragma unroll
;         for (int i = 0; i < PFD; ++i) a[i] = ld(i);
.LBB0_1148:
	s_cmp_gt_i32 s16, s40
	s_cbranch_scc1 .LBB0_1152
	v_add_u32_e32 v246, s12, v167
	v_add_u32_e32 v210, v246, v168
	ds_read_b128 v[196:199], v210
	ds_read_b128 v[202:205], v210 offset:4096
	ds_read_b128 v[206:209], v210 offset:8192
	ds_read_b128 v[210:213], v210 offset:12288
	v_add_u32_e32 v222, v246, v169
	ds_read_b128 v[214:217], v222
	ds_read_b128 v[218:221], v222 offset:4096
	v_mov_b32_e32 v179, 0x7f61b1e6
	s_nop 0
	v_med3_f32 v180, v18, v19, v179
	v_med3_f32 v184, v22, v23, v179
	v_med3_f32 v181, v20, v21, v179
	v_med3_f32 v180, v180, v184, v179
	v_med3_f32 v184, v24, v25, v179
	v_med3_f32 v182, v50, v51, v179
	v_med3_f32 v181, v181, v184, v179
	v_med3_f32 v184, v54, v55, v179
	v_med3_f32 v183, v52, v53, v179
	v_med3_f32 v182, v182, v184, v179
	v_med3_f32 v184, v56, v57, v179
	v_med3_f32 v183, v183, v184, v179
	v_med3_f32 v184, v26, v27, v179
	v_med3_f32 v180, v180, v184, v179
	v_med3_f32 v184, v28, v29, v179
	v_med3_f32 v181, v181, v184, v179
	v_med3_f32 v184, v58, v59, v179
	v_med3_f32 v182, v182, v184, v179
	v_med3_f32 v184, v60, v61, v179
	v_med3_f32 v183, v183, v184, v179
	v_med3_f32 v184, v30, v31, v179
	v_med3_f32 v180, v180, v184, v179
	v_med3_f32 v184, v32, v33, v179
	v_med3_f32 v181, v181, v184, v179
	v_med3_f32 v184, v62, v63, v179
	v_med3_f32 v182, v182, v184, v179
	v_med3_f32 v184, v64, v65, v179
	v_med3_f32 v183, v183, v184, v179
	v_med3_f32 v180, v180, v181, v179
	v_med3_f32 v181, v182, v183, v179
	v_and_b32_e32 v182, 64, v171
	v_med3_f32 v180, v180, v181, v179
	v_xor_b32_e32 v181, 32, v171
	v_add_u32_e32 v182, 64, v182
	v_cmp_lt_i32_e32 vcc, v181, v182
	s_nop 1
	v_cndmask_b32_e32 v181, v171, v181, vcc
	v_lshlrev_b32_e32 v181, 2, v181
	ds_bpermute_b32 v181, v181, v180
	s_waitcnt lgkmcnt(0)
	v_med3_f32 v179, v180, v181, v179
	v_add_f32_e32 v180, 0x41000000, v178
	v_cmp_gt_f32_e32 vcc, v179, v180
	s_cbranch_vccz .LBB0_1151
	v_max_f32_e32 v179, v179, v179
	v_max_f32_e32 v180, v178, v178
	v_max_f32_e32 v179, v180, v179
	v_sub_f32_e32 v178, v178, v179
	v_exp_f32_e32 v178, v178
	s_nop 0
	v_mul_f32_e32 v176, v176, v178
	v_pk_mul_f32 v[96:97], v[96:97], v[178:179] op_sel_hi:[1,0]
	v_pk_mul_f32 v[94:95], v[94:95], v[178:179] op_sel_hi:[1,0]
	v_pk_mul_f32 v[92:93], v[92:93], v[178:179] op_sel_hi:[1,0]
	v_pk_mul_f32 v[90:91], v[90:91], v[178:179] op_sel_hi:[1,0]
	v_pk_mul_f32 v[88:89], v[88:89], v[178:179] op_sel_hi:[1,0]
	v_pk_mul_f32 v[86:87], v[86:87], v[178:179] op_sel_hi:[1,0]
	v_pk_mul_f32 v[84:85], v[84:85], v[178:179] op_sel_hi:[1,0]
	v_pk_mul_f32 v[82:83], v[82:83], v[178:179] op_sel_hi:[1,0]
	v_pk_mul_f32 v[80:81], v[80:81], v[178:179] op_sel_hi:[1,0]
	v_pk_mul_f32 v[78:79], v[78:79], v[178:179] op_sel_hi:[1,0]
	v_pk_mul_f32 v[76:77], v[76:77], v[178:179] op_sel_hi:[1,0]
	v_pk_mul_f32 v[74:75], v[74:75], v[178:179] op_sel_hi:[1,0]
	v_pk_mul_f32 v[72:73], v[72:73], v[178:179] op_sel_hi:[1,0]
	v_pk_mul_f32 v[70:71], v[70:71], v[178:179] op_sel_hi:[1,0]
	v_pk_mul_f32 v[68:69], v[68:69], v[178:179] op_sel_hi:[1,0]
	v_pk_mul_f32 v[66:67], v[66:67], v[178:179] op_sel_hi:[1,0]
	v_pk_mul_f32 v[48:49], v[48:49], v[178:179] op_sel_hi:[1,0]
	v_pk_mul_f32 v[46:47], v[46:47], v[178:179] op_sel_hi:[1,0]
	v_pk_mul_f32 v[44:45], v[44:45], v[178:179] op_sel_hi:[1,0]
	v_pk_mul_f32 v[42:43], v[42:43], v[178:179] op_sel_hi:[1,0]
	v_pk_mul_f32 v[40:41], v[40:41], v[178:179] op_sel_hi:[1,0]
	v_pk_mul_f32 v[38:39], v[38:39], v[178:179] op_sel_hi:[1,0]
	v_pk_mul_f32 v[36:37], v[36:37], v[178:179] op_sel_hi:[1,0]
	v_pk_mul_f32 v[34:35], v[34:35], v[178:179] op_sel_hi:[1,0]
	v_pk_mul_f32 v[16:17], v[16:17], v[178:179] op_sel_hi:[1,0]
	v_pk_mul_f32 v[14:15], v[14:15], v[178:179] op_sel_hi:[1,0]
	v_pk_mul_f32 v[12:13], v[12:13], v[178:179] op_sel_hi:[1,0]
	v_pk_mul_f32 v[10:11], v[10:11], v[178:179] op_sel_hi:[1,0]
	v_pk_mul_f32 v[8:9], v[8:9], v[178:179] op_sel_hi:[1,0]
	v_pk_mul_f32 v[6:7], v[6:7], v[178:179] op_sel_hi:[1,0]
	v_pk_mul_f32 v[4:5], v[4:5], v[178:179] op_sel_hi:[1,0]
	v_pk_mul_f32 v[2:3], v[2:3], v[178:179] op_sel_hi:[1,0]
	v_mov_b32_e32 v178, v179
; __device__ __forceinline__ unsigned cvt_pk_bf16(float lo, float hi) { unsigned r; asm volatile("v_cvt_pk_bf16_f32 %0, %1, %2" : "=v"(r) : "v"(lo), "v"(hi)); return r; }
; #define LAS __attribute__((address_space(3)))
; template <bool MLA, bool grpB>
; __device__ __forceinline__ void attn_unit_g(LAS unsigned char* lds, const AttnPtrs& P, int b, int h, int qblk) {
;     ...
;         float ps = 0.f;
; #pragma unroll
;         for (int blk = 0; blk < 2; ++blk)
; #pragma unroll
;             for (int r = 0; r < 16; ++r) { const float pv_ = __builtin_amdgcn_exp2f(sc[blk][r] - mref); sc[blk][r] = pv_; ps += pv_; }
;         lrun += ps;
; #pragma unroll
;         for (int blk = 0; blk < 2; ++blk)
; #pragma unroll
;             for (int ks = 0; ks < 2; ++ks) { u32x4 w;
;                 w.x = pg8::cvt_pk_bf16(sc[blk][8 * ks + 0], sc[blk][8 * ks + 1]); w.y = pg8::cvt_pk_bf16(sc[blk][8 * ks + 2], sc[blk][8 * ks + 3]);
;                 w.z = pg8::cvt_pk_bf16(sc[blk][8 * ks + 4], sc[blk][8 * ks + 5]); w.w = pg8::cvt_pk_bf16(sc[blk][8 * ks + 6], sc[blk][8 * ks + 7]);
;                 pb[blk][ks] = __builtin_bit_cast(bf16x8, w); }
;         __builtin_amdgcn_sched_barrier(0);
;     };
;     auto pv = [&](int voff) {
;         const LAS unsigned char* va = lds + varow + voff;
;         bf16x8 a[PFD];
;         auto ld = [&](int i) -> bf16x8 {
;             const int dvb = i & 3, bk = i >> 2, so = ((4 * (bk >> 1) + 2 * hi + (bk & 1)) ^ vswz) * 16;
;             return *(const LAS bf16x8*)(va + 32 * dvb * VROW + so);
;         };
; #pragma unroll
;         for (int i = 0; i < PFD; ++i) a[i] = ld(i);
; #pragma unroll
;         for (int i = 0; i < 16; ++i) {
;             o[i & 3] = __builtin_amdgcn_mfma_f32_32x32x16_bf16(a[i % PFD], pb[i >> 3][(i >> 2) & 1], o[i & 3], 0, 0, 0);
;             if (i + PFD < 16) a[i % PFD] = ld(i + PFD);
;         }
;         __builtin_amdgcn_sched_group_barrier(0x100, PFD, 0);
; #pragma unroll
;         for (int i = 0; i < 16; ++i) { __builtin_amdgcn_sched_group_barrier(0x008, 1, 0); __builtin_amdgcn_sched_group_barrier(0x100, 1, 0); }
;         __builtin_amdgcn_sched_barrier(0);
.LBB0_1151:
	v_sub_f32_e32 v18, v18, v178
	v_exp_f32_e32 v18, v18
	v_sub_f32_e32 v19, v19, v178
	v_exp_f32_e32 v19, v19
	v_sub_f32_e32 v20, v20, v178
	v_exp_f32_e32 v20, v20
	v_sub_f32_e32 v21, v21, v178
	v_exp_f32_e32 v21, v21
	v_sub_f32_e32 v22, v22, v178
	v_add_f32_e32 v179, 0, v18
	v_exp_f32_e32 v22, v22
	v_sub_f32_e32 v23, v23, v178
	v_add_f32_e32 v179, v19, v179
	v_exp_f32_e32 v23, v23
	v_sub_f32_e32 v24, v24, v178
	v_add_f32_e32 v179, v20, v179
	v_exp_f32_e32 v24, v24
	v_sub_f32_e32 v25, v25, v178
	v_add_f32_e32 v179, v21, v179
	v_exp_f32_e32 v25, v25
	v_sub_f32_e32 v26, v26, v178
	v_add_f32_e32 v179, v22, v179
	v_exp_f32_e32 v26, v26
	v_sub_f32_e32 v27, v27, v178
	v_add_f32_e32 v179, v23, v179
	v_exp_f32_e32 v27, v27
	v_sub_f32_e32 v28, v28, v178
	v_add_f32_e32 v179, v24, v179
	v_exp_f32_e32 v28, v28
	v_sub_f32_e32 v29, v29, v178
	v_add_f32_e32 v179, v25, v179
	v_exp_f32_e32 v29, v29
	v_sub_f32_e32 v30, v30, v178
	v_add_f32_e32 v179, v26, v179
	v_exp_f32_e32 v30, v30
	v_sub_f32_e32 v31, v31, v178
	v_add_f32_e32 v179, v27, v179
	v_exp_f32_e32 v31, v31
	v_sub_f32_e32 v32, v32, v178
	v_add_f32_e32 v179, v28, v179
	v_exp_f32_e32 v32, v32
	v_sub_f32_e32 v33, v33, v178
	v_add_f32_e32 v179, v29, v179
	v_exp_f32_e32 v33, v33
	v_sub_f32_e32 v50, v50, v178
	v_add_f32_e32 v179, v30, v179
	v_exp_f32_e32 v50, v50
	v_sub_f32_e32 v51, v51, v178
	v_add_f32_e32 v179, v31, v179
	v_exp_f32_e32 v51, v51
	v_sub_f32_e32 v52, v52, v178
	v_add_f32_e32 v179, v32, v179
	v_exp_f32_e32 v52, v52
	v_sub_f32_e32 v53, v53, v178
	v_add_f32_e32 v179, v33, v179
	v_exp_f32_e32 v53, v53
	v_sub_f32_e32 v54, v54, v178
	v_add_f32_e32 v179, v50, v179
	v_exp_f32_e32 v54, v54
	v_sub_f32_e32 v55, v55, v178
	v_add_f32_e32 v179, v51, v179
	v_exp_f32_e32 v55, v55
	v_sub_f32_e32 v56, v56, v178
	v_add_f32_e32 v179, v52, v179
	v_exp_f32_e32 v56, v56
	v_sub_f32_e32 v57, v57, v178
	v_add_f32_e32 v179, v53, v179
	v_exp_f32_e32 v57, v57
	v_sub_f32_e32 v58, v58, v178
	v_add_f32_e32 v179, v54, v179
	v_exp_f32_e32 v58, v58
	v_sub_f32_e32 v59, v59, v178
	v_add_f32_e32 v179, v55, v179
	v_exp_f32_e32 v59, v59
	v_sub_f32_e32 v60, v60, v178
	v_add_f32_e32 v179, v56, v179
	v_exp_f32_e32 v60, v60
	v_sub_f32_e32 v61, v61, v178
	v_add_f32_e32 v179, v57, v179
	v_exp_f32_e32 v61, v61
	v_sub_f32_e32 v62, v62, v178
	v_add_f32_e32 v179, v58, v179
	v_exp_f32_e32 v62, v62
	v_sub_f32_e32 v63, v63, v178
	v_add_f32_e32 v179, v59, v179
	v_exp_f32_e32 v63, v63
	v_sub_f32_e32 v64, v64, v178
	v_add_f32_e32 v179, v60, v179
	v_exp_f32_e32 v64, v64
	v_sub_f32_e32 v65, v65, v178
	v_add_f32_e32 v179, v61, v179
	v_exp_f32_e32 v65, v65
	v_add_f32_e32 v179, v62, v179
	v_add_f32_e32 v179, v63, v179
	v_add_f32_e32 v179, v64, v179
	v_add_f32_e32 v179, v65, v179
	v_add_f32_e32 v176, v176, v179
	v_cvt_pk_bf16_f32 v180, v18, v19
	v_cvt_pk_bf16_f32 v181, v20, v21
	v_cvt_pk_bf16_f32 v182, v22, v23
	v_cvt_pk_bf16_f32 v183, v24, v25
	v_cvt_pk_bf16_f32 v184, v26, v27
	v_cvt_pk_bf16_f32 v185, v28, v29
	v_cvt_pk_bf16_f32 v186, v30, v31
	v_cvt_pk_bf16_f32 v187, v32, v33
	v_cvt_pk_bf16_f32 v188, v50, v51
	v_cvt_pk_bf16_f32 v189, v52, v53
	v_cvt_pk_bf16_f32 v190, v54, v55
	v_cvt_pk_bf16_f32 v191, v56, v57
	v_cvt_pk_bf16_f32 v192, v58, v59
	v_cvt_pk_bf16_f32 v193, v60, v61
	v_cvt_pk_bf16_f32 v194, v62, v63
	v_cvt_pk_bf16_f32 v195, v64, v65
	s_waitcnt lgkmcnt(5)
	s_setprio 1
	v_mfma_f32_32x32x16_bf16 v[82:97], v[196:199], v[180:183], v[82:97]
	ds_read_b128 v[196:199], v222 offset:8192
	s_waitcnt lgkmcnt(5)
	v_mfma_f32_32x32x16_bf16 v[66:81], v[202:205], v[180:183], v[66:81]
	ds_read_b128 v[202:205], v222 offset:12288
	v_add_u32_e32 v222, v246, v175
	v_add_u32_e32 v179, v246, v177
	s_waitcnt lgkmcnt(5)
	v_mfma_f32_32x32x16_bf16 v[34:49], v[206:209], v[180:183], v[34:49]
	ds_read_b128 v[206:209], v222
	s_waitcnt lgkmcnt(5)
	v_mfma_f32_32x32x16_bf16 v[2:17], v[210:213], v[180:183], v[2:17]
	ds_read_b128 v[180:183], v222 offset:4096
	s_waitcnt lgkmcnt(5)
	v_mfma_f32_32x32x16_bf16 v[82:97], v[214:217], v[184:187], v[82:97]
	ds_read_b128 v[210:213], v222 offset:8192
	s_waitcnt lgkmcnt(5)
	v_mfma_f32_32x32x16_bf16 v[66:81], v[218:221], v[184:187], v[66:81]
	ds_read_b128 v[214:217], v222 offset:12288
	s_waitcnt lgkmcnt(5)
	v_mfma_f32_32x32x16_bf16 v[34:49], v[196:199], v[184:187], v[34:49]
	ds_read_b128 v[196:199], v179
	s_waitcnt lgkmcnt(5)
	v_mfma_f32_32x32x16_bf16 v[2:17], v[202:205], v[184:187], v[2:17]
	ds_read_b128 v[184:187], v179 offset:4096
	s_waitcnt lgkmcnt(5)
	v_mfma_f32_32x32x16_bf16 v[82:97], v[206:209], v[188:191], v[82:97]
	ds_read_b128 v[202:205], v179 offset:8192
	s_waitcnt lgkmcnt(5)
	v_mfma_f32_32x32x16_bf16 v[66:81], v[180:183], v[188:191], v[66:81]
	ds_read_b128 v[180:183], v179 offset:12288
	s_waitcnt lgkmcnt(5)
	v_mfma_f32_32x32x16_bf16 v[34:49], v[210:213], v[188:191], v[34:49]
	s_waitcnt lgkmcnt(4)
	v_mfma_f32_32x32x16_bf16 v[2:17], v[214:217], v[188:191], v[2:17]
	s_waitcnt lgkmcnt(3)
	v_mfma_f32_32x32x16_bf16 v[82:97], v[196:199], v[192:195], v[82:97]
	s_waitcnt lgkmcnt(2)
	v_mfma_f32_32x32x16_bf16 v[66:81], v[184:187], v[192:195], v[66:81]
	s_waitcnt lgkmcnt(1)
	v_mfma_f32_32x32x16_bf16 v[34:49], v[202:205], v[192:195], v[34:49]
	s_waitcnt lgkmcnt(0)
	v_mfma_f32_32x32x16_bf16 v[2:17], v[180:183], v[192:195], v[2:17]
	s_setprio 0

; #define LAS __attribute__((address_space(3)))
; #define MAX2(a, b) __builtin_amdgcn_fmed3f((a), (b), big_)
; template <bool MLA, bool grpB>
; __device__ __forceinline__ void attn_unit_g(LAS unsigned char* lds, const AttnPtrs& P, int b, int h, int qblk) {
;     ...
;         float big_ = 3.0e38f; asm volatile("" : "+v"(big_));
;         float mxa = MAX2(sc[0][0], sc[0][1]), mxb = MAX2(sc[0][2], sc[0][3]), mxc = MAX2(sc[1][0], sc[1][1]), mxd = MAX2(sc[1][2], sc[1][3]);
; #pragma unroll
;         for (int r = 4; r < 16; r += 4) { mxa = MAX2(mxa, MAX2(sc[0][r], sc[0][r + 1])); mxb = MAX2(mxb, MAX2(sc[0][r + 2], sc[0][r + 3])); mxc = MAX2(mxc, MAX2(sc[1][r], sc[1][r + 1])); mxd = MAX2(mxd, MAX2(sc[1][r + 2], sc[1][r + 3])); }
;         float mx = MAX2(MAX2(mxa, mxb), MAX2(mxc, mxd));
;         mx = MAX2(mx, __shfl_xor(mx, 32));
;         if (__any(mx > mref + 8.0f)) {
;             const float mnew = fmaxf(mref, mx), f = __builtin_amdgcn_exp2f(mref - mnew);
;             mref = mnew; lrun *= f;
; #pragma unroll
;             for (int i = 0; i < 4; ++i)
; #pragma unroll
;                 for (int r = 0; r < 16; ++r) o[i][r] *= f;
;         }
;     ...
;     auto pv = [&](int voff) {
;         const LAS unsigned char* va = lds + varow + voff;
;         bf16x8 a[PFD];
;         auto ld = [&](int i) -> bf16x8 {
;             const int dvb = i & 3, bk = i >> 2, so = ((4 * (bk >> 1) + 2 * hi + (bk & 1)) ^ vswz) * 16;
;             return *(const LAS bf16x8*)(va + 32 * dvb * VROW + so);
;         };
; #pragma unroll
;         for (int i = 0; i < PFD; ++i) a[i] = ld(i);
.LBB0_1266:
	v_add_u32_e32 v246, s54, v175
	v_add_u32_e32 v14, v246, v176
	ds_read_b128 v[186:189], v14
	ds_read_b128 v[190:193], v14 offset:4096
	ds_read_b128 v[194:197], v14 offset:8192
	ds_read_b128 v[202:205], v14 offset:12288
	v_add_u32_e32 v15, v246, v177
	ds_read_b128 v[206:209], v15
	ds_read_b128 v[210:213], v15 offset:4096
	v_mov_b32_e32 v0, 0x7f61b1e6
	s_nop 0
	v_med3_f32 v2, v16, v17, v0
	v_med3_f32 v6, v20, v21, v0
	v_med3_f32 v3, v18, v19, v0
	v_med3_f32 v2, v2, v6, v0
	v_med3_f32 v6, v22, v23, v0
	v_med3_f32 v4, v32, v33, v0
	v_med3_f32 v3, v3, v6, v0
	v_med3_f32 v6, v36, v37, v0
	v_med3_f32 v5, v34, v35, v0
	v_med3_f32 v4, v4, v6, v0
	v_med3_f32 v6, v38, v39, v0
	v_med3_f32 v5, v5, v6, v0
	v_med3_f32 v6, v24, v25, v0
	v_med3_f32 v2, v2, v6, v0
	v_med3_f32 v6, v26, v27, v0
	v_med3_f32 v3, v3, v6, v0
	v_med3_f32 v6, v40, v41, v0
	v_med3_f32 v4, v4, v6, v0
	v_med3_f32 v6, v42, v43, v0
	v_med3_f32 v5, v5, v6, v0
	v_med3_f32 v6, v28, v29, v0
	v_med3_f32 v2, v2, v6, v0
	v_med3_f32 v6, v30, v31, v0
	v_med3_f32 v3, v3, v6, v0
	v_med3_f32 v6, v44, v45, v0
	v_med3_f32 v4, v4, v6, v0
	v_med3_f32 v6, v46, v47, v0
	v_med3_f32 v5, v5, v6, v0
	v_med3_f32 v2, v2, v3, v0
	v_med3_f32 v3, v4, v5, v0
	v_and_b32_e32 v4, 64, v171
	v_med3_f32 v2, v2, v3, v0
	v_xor_b32_e32 v3, 32, v171
	v_add_u32_e32 v4, 64, v4
	v_cmp_lt_i32_e32 vcc, v3, v4
	s_nop 1
	v_cndmask_b32_e32 v3, v171, v3, vcc
	v_lshlrev_b32_e32 v3, 2, v3
	ds_bpermute_b32 v3, v3, v2
	s_waitcnt lgkmcnt(0)
	v_med3_f32 v0, v2, v3, v0
	v_add_f32_e32 v2, 0x41000000, v181
	v_cmp_gt_f32_e32 vcc, v0, v2
	s_cbranch_vccz .LBB0_1268
	v_max_f32_e32 v0, v0, v0
	v_max_f32_e32 v2, v181, v181
	v_max_f32_e32 v2, v2, v0
	v_sub_f32_e32 v0, v181, v2
	v_exp_f32_e32 v0, v0
	v_mov_b32_e32 v181, v2
	v_mul_f32_e32 v180, v180, v0
	v_pk_mul_f32 v[110:111], v[110:111], v[0:1] op_sel_hi:[1,0]
	v_pk_mul_f32 v[108:109], v[108:109], v[0:1] op_sel_hi:[1,0]
	v_pk_mul_f32 v[106:107], v[106:107], v[0:1] op_sel_hi:[1,0]
	v_pk_mul_f32 v[104:105], v[104:105], v[0:1] op_sel_hi:[1,0]
	v_pk_mul_f32 v[102:103], v[102:103], v[0:1] op_sel_hi:[1,0]
	v_pk_mul_f32 v[100:101], v[100:101], v[0:1] op_sel_hi:[1,0]
	v_pk_mul_f32 v[98:99], v[98:99], v[0:1] op_sel_hi:[1,0]
	v_pk_mul_f32 v[96:97], v[96:97], v[0:1] op_sel_hi:[1,0]
	v_pk_mul_f32 v[94:95], v[94:95], v[0:1] op_sel_hi:[1,0]
	v_pk_mul_f32 v[92:93], v[92:93], v[0:1] op_sel_hi:[1,0]
	v_pk_mul_f32 v[90:91], v[90:91], v[0:1] op_sel_hi:[1,0]
	v_pk_mul_f32 v[88:89], v[88:89], v[0:1] op_sel_hi:[1,0]
	v_pk_mul_f32 v[86:87], v[86:87], v[0:1] op_sel_hi:[1,0]
	v_pk_mul_f32 v[84:85], v[84:85], v[0:1] op_sel_hi:[1,0]
	v_pk_mul_f32 v[82:83], v[82:83], v[0:1] op_sel_hi:[1,0]
	v_pk_mul_f32 v[80:81], v[80:81], v[0:1] op_sel_hi:[1,0]
	v_pk_mul_f32 v[78:79], v[78:79], v[0:1] op_sel_hi:[1,0]
	v_pk_mul_f32 v[76:77], v[76:77], v[0:1] op_sel_hi:[1,0]
	v_pk_mul_f32 v[74:75], v[74:75], v[0:1] op_sel_hi:[1,0]
	v_pk_mul_f32 v[72:73], v[72:73], v[0:1] op_sel_hi:[1,0]
	v_pk_mul_f32 v[70:71], v[70:71], v[0:1] op_sel_hi:[1,0]
	v_pk_mul_f32 v[68:69], v[68:69], v[0:1] op_sel_hi:[1,0]
	v_pk_mul_f32 v[66:67], v[66:67], v[0:1] op_sel_hi:[1,0]
	v_pk_mul_f32 v[64:65], v[64:65], v[0:1] op_sel_hi:[1,0]
	v_pk_mul_f32 v[62:63], v[62:63], v[0:1] op_sel_hi:[1,0]
	v_pk_mul_f32 v[60:61], v[60:61], v[0:1] op_sel_hi:[1,0]
	v_pk_mul_f32 v[58:59], v[58:59], v[0:1] op_sel_hi:[1,0]
	v_pk_mul_f32 v[56:57], v[56:57], v[0:1] op_sel_hi:[1,0]
	v_pk_mul_f32 v[54:55], v[54:55], v[0:1] op_sel_hi:[1,0]
	v_pk_mul_f32 v[52:53], v[52:53], v[0:1] op_sel_hi:[1,0]
	v_pk_mul_f32 v[50:51], v[50:51], v[0:1] op_sel_hi:[1,0]
	v_pk_mul_f32 v[48:49], v[48:49], v[0:1] op_sel_hi:[1,0]
; __device__ __forceinline__ unsigned cvt_pk_bf16(float lo, float hi) { unsigned r; asm volatile("v_cvt_pk_bf16_f32 %0, %1, %2" : "=v"(r) : "v"(lo), "v"(hi)); return r; }
; #define LAS __attribute__((address_space(3)))
; template <bool MLA, bool grpB>
; __device__ __forceinline__ void attn_unit_g(LAS unsigned char* lds, const AttnPtrs& P, int b, int h, int qblk) {
;     ...
;         float ps = 0.f;
; #pragma unroll
;         for (int blk = 0; blk < 2; ++blk)
; #pragma unroll
;             for (int r = 0; r < 16; ++r) { const float pv_ = __builtin_amdgcn_exp2f(sc[blk][r] - mref); sc[blk][r] = pv_; ps += pv_; }
;         lrun += ps;
; #pragma unroll
;         for (int blk = 0; blk < 2; ++blk)
; #pragma unroll
;             for (int ks = 0; ks < 2; ++ks) { u32x4 w;
;                 w.x = pg8::cvt_pk_bf16(sc[blk][8 * ks + 0], sc[blk][8 * ks + 1]); w.y = pg8::cvt_pk_bf16(sc[blk][8 * ks + 2], sc[blk][8 * ks + 3]);
;                 w.z = pg8::cvt_pk_bf16(sc[blk][8 * ks + 4], sc[blk][8 * ks + 5]); w.w = pg8::cvt_pk_bf16(sc[blk][8 * ks + 6], sc[blk][8 * ks + 7]);
;                 pb[blk][ks] = __builtin_bit_cast(bf16x8, w); }
;         __builtin_amdgcn_sched_barrier(0);
;     };
;     auto pv = [&](int voff) {
;         const LAS unsigned char* va = lds + varow + voff;
;         bf16x8 a[PFD];
;         auto ld = [&](int i) -> bf16x8 {
;             const int dvb = i & 3, bk = i >> 2, so = ((4 * (bk >> 1) + 2 * hi + (bk & 1)) ^ vswz) * 16;
;             return *(const LAS bf16x8*)(va + 32 * dvb * VROW + so);
;         };
; #pragma unroll
;         for (int i = 0; i < PFD; ++i) a[i] = ld(i);
; #pragma unroll
;         for (int i = 0; i < 16; ++i) {
;             o[i & 3] = __builtin_amdgcn_mfma_f32_32x32x16_bf16(a[i % PFD], pb[i >> 3][(i >> 2) & 1], o[i & 3], 0, 0, 0);
;             if (i + PFD < 16) a[i % PFD] = ld(i + PFD);
;         }
;         __builtin_amdgcn_sched_group_barrier(0x100, PFD, 0);
; #pragma unroll
;         for (int i = 0; i < 16; ++i) { __builtin_amdgcn_sched_group_barrier(0x008, 1, 0); __builtin_amdgcn_sched_group_barrier(0x100, 1, 0); }
;         __builtin_amdgcn_sched_barrier(0);
.LBB0_1268:
	v_sub_f32_e32 v0, v16, v181
	v_exp_f32_e32 v16, v0
	v_sub_f32_e32 v0, v17, v181
	v_exp_f32_e32 v17, v0
	v_sub_f32_e32 v0, v18, v181
	v_exp_f32_e32 v18, v0
	v_sub_f32_e32 v0, v19, v181
	v_exp_f32_e32 v19, v0
	v_sub_f32_e32 v2, v20, v181
	v_add_f32_e32 v0, 0, v16
	v_exp_f32_e32 v20, v2
	v_sub_f32_e32 v2, v21, v181
	v_add_f32_e32 v0, v17, v0
	v_exp_f32_e32 v21, v2
	v_sub_f32_e32 v2, v22, v181
	v_add_f32_e32 v0, v18, v0
	v_exp_f32_e32 v22, v2
	v_sub_f32_e32 v2, v23, v181
	v_add_f32_e32 v0, v19, v0
	v_exp_f32_e32 v23, v2
	v_sub_f32_e32 v2, v24, v181
	v_add_f32_e32 v0, v20, v0
	v_exp_f32_e32 v24, v2
	v_sub_f32_e32 v2, v25, v181
	v_add_f32_e32 v0, v21, v0
	v_exp_f32_e32 v25, v2
	v_sub_f32_e32 v2, v26, v181
	v_add_f32_e32 v0, v22, v0
	v_exp_f32_e32 v26, v2
	v_sub_f32_e32 v2, v27, v181
	v_add_f32_e32 v0, v23, v0
	v_exp_f32_e32 v27, v2
	v_sub_f32_e32 v2, v28, v181
	v_add_f32_e32 v0, v24, v0
	v_exp_f32_e32 v28, v2
	v_sub_f32_e32 v2, v29, v181
	v_add_f32_e32 v0, v25, v0
	v_exp_f32_e32 v29, v2
	v_sub_f32_e32 v2, v30, v181
	v_add_f32_e32 v0, v26, v0
	v_exp_f32_e32 v30, v2
	v_sub_f32_e32 v2, v31, v181
	v_add_f32_e32 v0, v27, v0
	v_exp_f32_e32 v31, v2
	v_sub_f32_e32 v2, v32, v181
	v_add_f32_e32 v0, v28, v0
	v_exp_f32_e32 v32, v2
	v_sub_f32_e32 v2, v33, v181
	v_add_f32_e32 v0, v29, v0
	v_exp_f32_e32 v33, v2
	v_sub_f32_e32 v2, v34, v181
	v_add_f32_e32 v0, v30, v0
	v_exp_f32_e32 v34, v2
	v_sub_f32_e32 v2, v35, v181
	v_add_f32_e32 v0, v31, v0
	v_exp_f32_e32 v35, v2
	v_sub_f32_e32 v2, v36, v181
	v_add_f32_e32 v0, v32, v0
	v_exp_f32_e32 v36, v2
	v_sub_f32_e32 v2, v37, v181
	v_add_f32_e32 v0, v33, v0
	v_exp_f32_e32 v37, v2
	v_sub_f32_e32 v2, v38, v181
	v_add_f32_e32 v0, v34, v0
	v_exp_f32_e32 v38, v2
	v_sub_f32_e32 v2, v39, v181
	v_add_f32_e32 v0, v35, v0
	v_exp_f32_e32 v39, v2
	v_sub_f32_e32 v2, v40, v181
	v_add_f32_e32 v0, v36, v0
	v_exp_f32_e32 v40, v2
	v_sub_f32_e32 v2, v41, v181
	v_add_f32_e32 v0, v37, v0
	v_exp_f32_e32 v41, v2
	v_sub_f32_e32 v2, v42, v181
	v_add_f32_e32 v0, v38, v0
	v_exp_f32_e32 v42, v2
	v_sub_f32_e32 v2, v43, v181
	v_add_f32_e32 v0, v39, v0
	v_exp_f32_e32 v43, v2
	v_sub_f32_e32 v2, v44, v181
	v_add_f32_e32 v0, v40, v0
	v_exp_f32_e32 v44, v2
	v_sub_f32_e32 v2, v45, v181
	v_add_f32_e32 v0, v41, v0
	v_exp_f32_e32 v45, v2
	v_sub_f32_e32 v2, v46, v181
	v_add_f32_e32 v0, v42, v0
	v_exp_f32_e32 v46, v2
	v_sub_f32_e32 v2, v47, v181
	v_add_f32_e32 v0, v43, v0
	v_exp_f32_e32 v47, v2
	v_add_f32_e32 v0, v44, v0
	v_add_f32_e32 v0, v45, v0
	v_add_f32_e32 v0, v46, v0
	v_add_f32_e32 v0, v47, v0
	v_add_f32_e32 v180, v180, v0
	v_cvt_pk_bf16_f32 v2, v16, v17
	v_cvt_pk_bf16_f32 v3, v18, v19
	v_cvt_pk_bf16_f32 v4, v20, v21
	v_cvt_pk_bf16_f32 v5, v22, v23
	v_cvt_pk_bf16_f32 v6, v24, v25
	v_cvt_pk_bf16_f32 v7, v26, v27
	v_cvt_pk_bf16_f32 v8, v28, v29
	v_cvt_pk_bf16_f32 v9, v30, v31
	v_cvt_pk_bf16_f32 v10, v32, v33
	v_cvt_pk_bf16_f32 v11, v34, v35
	v_cvt_pk_bf16_f32 v12, v36, v37
	v_cvt_pk_bf16_f32 v13, v38, v39
	v_cvt_pk_bf16_f32 v182, v40, v41
	v_cvt_pk_bf16_f32 v183, v42, v43
	v_cvt_pk_bf16_f32 v184, v44, v45
	v_cvt_pk_bf16_f32 v185, v46, v47
	v_add_u32_e32 v14, v246, v178
	v_add_u32_e32 v0, v246, v179
	s_waitcnt lgkmcnt(5)
	s_setprio 1
	v_mfma_f32_32x32x16_bf16 v[96:111], v[186:189], v[2:5], v[96:111]
	ds_read_b128 v[186:189], v15 offset:8192
	s_waitcnt lgkmcnt(5)
	v_mfma_f32_32x32x16_bf16 v[80:95], v[190:193], v[2:5], v[80:95]
	ds_read_b128 v[190:193], v15 offset:12288
	s_waitcnt lgkmcnt(5)
	v_mfma_f32_32x32x16_bf16 v[64:79], v[194:197], v[2:5], v[64:79]
	ds_read_b128 v[194:197], v14
	s_waitcnt lgkmcnt(5)
	v_mfma_f32_32x32x16_bf16 v[48:63], v[202:205], v[2:5], v[48:63]
	ds_read_b128 v[2:5], v14 offset:4096
	s_waitcnt lgkmcnt(5)
	v_mfma_f32_32x32x16_bf16 v[96:111], v[206:209], v[6:9], v[96:111]
	ds_read_b128 v[202:205], v14 offset:8192
	s_waitcnt lgkmcnt(5)
	v_mfma_f32_32x32x16_bf16 v[80:95], v[210:213], v[6:9], v[80:95]
	ds_read_b128 v[206:209], v14 offset:12288
	s_waitcnt lgkmcnt(5)
	v_mfma_f32_32x32x16_bf16 v[64:79], v[186:189], v[6:9], v[64:79]
	ds_read_b128 v[186:189], v0
	s_waitcnt lgkmcnt(5)
	v_mfma_f32_32x32x16_bf16 v[48:63], v[190:193], v[6:9], v[48:63]
	ds_read_b128 v[6:9], v0 offset:4096
	s_waitcnt lgkmcnt(5)
	v_mfma_f32_32x32x16_bf16 v[96:111], v[194:197], v[10:13], v[96:111]
	ds_read_b128 v[190:193], v0 offset:8192
	s_waitcnt lgkmcnt(5)
	v_mfma_f32_32x32x16_bf16 v[80:95], v[2:5], v[10:13], v[80:95]
	ds_read_b128 v[2:5], v0 offset:12288
	s_waitcnt lgkmcnt(5)
	v_mfma_f32_32x32x16_bf16 v[64:79], v[202:205], v[10:13], v[64:79]
	s_waitcnt lgkmcnt(4)
	v_mfma_f32_32x32x16_bf16 v[48:63], v[206:209], v[10:13], v[48:63]
	s_waitcnt lgkmcnt(3)
	v_mfma_f32_32x32x16_bf16 v[96:111], v[186:189], v[182:185], v[96:111]
	s_waitcnt lgkmcnt(2)
	v_mfma_f32_32x32x16_bf16 v[80:95], v[6:9], v[182:185], v[80:95]
	s_waitcnt lgkmcnt(1)
	v_mfma_f32_32x32x16_bf16 v[64:79], v[190:193], v[182:185], v[64:79]
	s_waitcnt lgkmcnt(0)
	v_mfma_f32_32x32x16_bf16 v[48:63], v[2:5], v[182:185], v[48:63]
	s_setprio 0
